# dilated attention: K/V tile row addresses via one v_mad_u32_u24 + saddr loads instead of two v_mad_i64_i32 per row
# baseline (speedup 1.0000x reference)
; DI void row_info(int m, int& seq_lo, int& S) { if (m < M_P) { seq_lo = m & ~8191; S = 8192; } else { seq_lo = M_P + ((m - M_P) & ~4095); S = 4096; } }
; #define DIL_LOAD(KF, VR, TIV) do { int d_, u_; dil_tile_info((TIV), m0, d_, u_); \
;       const int ur_ = min(max(u_ + d_ * r32, seq_lo), seq_hi - 1); \
;       _Pragma("unroll") for (int i = 0; i < 4; ++i) { const int uv_ = min(max(u_ + d_ * (vrow + 8 * i), seq_lo), seq_hi - 1); VR[i] = *(const u32x4*)(vbaseg + (size_t)uv_ * 2560); KF[i] = *(const u32x4*)(kbase + (size_t)uv_ * 2560); } } while (0)
; DI void dilated_phase(const Params& p, char* lds, int gw, int nw) {
;     ...
;     const int m0 = sp * 512 + res;
;     int seq_lo, S; row_info(sp * 512, seq_lo, S); const int seq_hi = seq_lo + S;
;     const int mq = m0 + 16 * r32;
;     bf16x8 qf[4];
; #pragma unroll
;     for (int ks = 0; ks < 4; ++ks) qf[ks] = *(const bf16x8*)(PROJ + (size_t)mq * 2560 + 1024 + h * 64 + ks * 16 + 8 * hi);
;     const float slope2 = exp2f(-(float)(h + 1)) * LOG2E;
;     const float c1 = 0.125f * LOG2E;
;     float m_run = -1e30f, l_run = 0.f; f32x16 o0 = {}, o1 = {};
;     const u16* kbase = PROJ + 1536 + h * 64 + vch * 8;
;     const u16* vbaseg = PROJ + 2048 + h * 64 + vch * 8;
;     u32x4 kfA[4], kfB[4]; u32x4 vrA[4], vrB[4];
;     ...
;     DIL_LOAD(kfA, vrA, 0);
;     DIL_LOAD(kfB, vrB, 1);
.LBB0_375:
	s_lshl_b32 s29, s68, 9
	s_add_i32 s73, s4, s29
	s_and_b32 s28, s65, 7
	v_add_u32_e32 v156, s73, v165
	s_lshl_b32 s4, s28, 7
	v_mad_i64_i32 v[2:3], s[18:19], v156, s47, v[152:153]
	s_lshl_b32 s65, s28, 6
	v_lshl_add_u64 v[2:3], v[2:3], 0, s[4:5]
	s_cmp_lt_i32 s68, 64
	v_lshl_add_u64 v[2:3], v[2:3], 0, v[154:155]
	s_cselect_b32 s68, s46, 0x7ffff000
	v_lshl_add_u64 v[4:5], v[2:3], 0, s[8:9]
	v_add_co_u32_e32 v2, vcc, s52, v2
	s_cselect_b32 s69, s53, 0xfff
	s_add_i32 s28, s28, 1
	v_addc_co_u32_e32 v3, vcc, 0, v3, vcc
	v_cvt_f32_ubyte0_e32 v1, s28
	s_and_b32 s68, s68, s29
	v_cmp_lt_f32_e32 vcc, s56, v1
	s_and_b64 s[18:19], vcc, exec
	s_cselect_b32 s28, 0xffffffc0, 0
	v_lshl_add_u64 v[158:159], v[148:149], 0, s[4:5]
	v_lshl_add_u64 v[160:161], v[150:151], 0, s[4:5]
	v_subrev_u32_e32 v204, s24, v160
	s_add_i32 s4, s73, 0xfffffc00
	v_add_u32_e32 v7, s4, v166
	global_load_dwordx4 v[58:61], v[4:5], off offset:32
	global_load_dwordx4 v[54:57], v[4:5], off offset:64
	global_load_dwordx4 v[62:65], v[2:3], off offset:2048
	global_load_dwordx4 v[50:53], v[4:5], off offset:96
	s_add_i32 s69, s68, s69
	v_max_i32_e32 v2, s68, v7
	v_min_i32_e32 v4, s69, v2
	v_mad_i64_i32 v[2:3], s[18:19], v4, s47, v[160:161]
	v_mad_i64_i32 v[4:5], s[18:19], v4, s47, v[158:159]
	global_load_dwordx4 v[70:73], v[2:3], off
	global_load_dwordx4 v[66:69], v[4:5], off
	v_add_u32_e32 v2, 0x80, v7
	v_max_i32_e32 v2, s68, v2
	v_min_i32_e32 v4, s69, v2
	v_mad_i64_i32 v[2:3], s[18:19], v4, s47, v[160:161]
	v_mad_i64_i32 v[4:5], s[18:19], v4, s47, v[158:159]
	global_load_dwordx4 v[78:81], v[2:3], off
	global_load_dwordx4 v[74:77], v[4:5], off
	v_add_u32_e32 v2, 0x100, v7
	v_max_i32_e32 v2, s68, v2
	v_min_i32_e32 v4, s69, v2
	v_mad_i64_i32 v[2:3], s[18:19], v4, s47, v[160:161]
	v_mad_i64_i32 v[4:5], s[18:19], v4, s47, v[158:159]
	global_load_dwordx4 v[94:97], v[2:3], off
	global_load_dwordx4 v[90:93], v[4:5], off
	v_add_u32_e32 v2, 0x180, v7
	v_max_i32_e32 v2, s68, v2
	v_min_i32_e32 v4, s69, v2
	v_mad_i64_i32 v[2:3], s[18:19], v4, s47, v[160:161]
	v_add_u32_e32 v7, s73, v167
	v_mad_i64_i32 v[4:5], s[18:19], v4, s47, v[158:159]
	global_load_dwordx4 v[110:113], v[2:3], off
	global_load_dwordx4 v[106:109], v[4:5], off
	v_max_i32_e32 v2, s68, v7
	v_min_i32_e32 v4, s69, v2
	v_mad_i64_i32 v[2:3], s[18:19], v4, s47, v[160:161]
	v_mad_i64_i32 v[4:5], s[18:19], v4, s47, v[158:159]
	global_load_dwordx4 v[82:85], v[2:3], off
	global_load_dwordx4 v[86:89], v[4:5], off
	v_add_u32_e32 v2, 0x80, v7
	v_max_i32_e32 v2, s68, v2
	v_min_i32_e32 v4, s69, v2
	v_mad_i64_i32 v[2:3], s[18:19], v4, s47, v[160:161]
	v_mad_i64_i32 v[4:5], s[18:19], v4, s47, v[158:159]
	global_load_dwordx4 v[98:101], v[2:3], off
	global_load_dwordx4 v[102:105], v[4:5], off
	v_add_u32_e32 v2, 0x100, v7
	v_max_i32_e32 v2, s68, v2
	v_min_i32_e32 v4, s69, v2
	v_mad_i64_i32 v[2:3], s[18:19], v4, s47, v[160:161]
	v_mad_i64_i32 v[4:5], s[18:19], v4, s47, v[158:159]
	global_load_dwordx4 v[114:117], v[2:3], off
	global_load_dwordx4 v[118:121], v[4:5], off
	v_add_u32_e32 v2, 0x180, v7
	v_max_i32_e32 v2, s68, v2
	v_min_i32_e32 v4, s69, v2
	v_mad_i64_i32 v[2:3], s[18:19], v4, s47, v[160:161]
	v_mad_i64_i32 v[4:5], s[18:19], v4, s47, v[158:159]
	global_load_dwordx4 v[122:125], v[2:3], off
	global_load_dwordx4 v[126:129], v[4:5], off
	v_cndmask_b32_e32 v6, 0, v189, vcc
	v_sub_f32_e32 v1, v6, v1
	v_exp_f32_e32 v1, v1
	v_sub_u32_e32 v2, s68, v156
	v_cvt_f32_i32_e32 v16, v2
	v_sub_u32_e32 v2, s69, v156
	v_cvt_f32_i32_e32 v17, v2
	v_ldexp_f32 v1, v1, s28
	v_mov_b32_e32 v14, v0
	v_mov_b32_e32 v15, v0
	v_mul_f32_e32 v193, 0xbfb8aa3b, v1
	v_mov_b32_e32 v1, v0
	v_mov_b32_e32 v2, v0
	v_mov_b32_e32 v3, v0
	v_mov_b32_e32 v4, v0
	v_mov_b32_e32 v5, v0
	v_mov_b32_e32 v6, v0
	v_mov_b32_e32 v7, v0
	v_mov_b32_e32 v8, v0
	v_mov_b32_e32 v9, v0
	v_mov_b32_e32 v10, v0
	v_mov_b32_e32 v11, v0
	v_mov_b32_e32 v12, v0
	v_mov_b32_e32 v13, v0
	v_mov_b64_e32 v[32:33], v[14:15]
	v_max_f32_e32 v195, v16, v16
	v_max_f32_e32 v196, v17, v17
	v_mov_b64_e32 v[30:31], v[12:13]
	v_mov_b64_e32 v[28:29], v[10:11]
	v_mov_b64_e32 v[26:27], v[8:9]
	v_mov_b64_e32 v[24:25], v[6:7]
	v_mov_b64_e32 v[22:23], v[4:5]
	v_mov_b64_e32 v[20:21], v[2:3]
	v_mov_b64_e32 v[18:19], v[0:1]
	v_mov_b64_e32 v[16:17], v[14:15]
	v_ashrrev_i32_e32 v157, 31, v156
	s_mov_b32 s75, 0
	s_add_i32 s70, s73, 0xfffffe20
	s_add_i32 s71, s73, 0xfffffc80
	s_add_i32 s72, s73, 0x200
	s_addk_i32 s73, 0xfe00
	v_mov_b32_e32 v197, 0
	v_mov_b32_e32 v194, 0xf149f2ca
	v_mov_b64_e32 v[14:15], v[12:13]
	v_mov_b64_e32 v[12:13], v[10:11]
	v_mov_b64_e32 v[10:11], v[8:9]
	v_mov_b64_e32 v[8:9], v[6:7]
	v_mov_b64_e32 v[6:7], v[4:5]
	v_mov_b64_e32 v[4:5], v[2:3]
	v_mov_b64_e32 v[2:3], v[0:1]
.LBB0_376:
	s_waitcnt vmcnt(7)
	ds_write_b128 v190, v[70:73]
	s_waitcnt vmcnt(6)
	ds_write_b128 v191, v[66:69] offset:6144
	s_waitcnt vmcnt(5)
	ds_write_b128 v190, v[78:81] offset:1536
	s_waitcnt vmcnt(4)
	ds_write_b128 v191, v[74:77] offset:7296
	s_waitcnt vmcnt(3)
	ds_write_b128 v190, v[94:97] offset:3072
	s_waitcnt vmcnt(2)
	ds_write_b128 v191, v[90:93] offset:8448
	s_waitcnt vmcnt(1)
	ds_write_b128 v190, v[110:113] offset:4608
	s_waitcnt vmcnt(0)
	ds_write_b128 v191, v[106:109] offset:9600
	ds_read_b128 v[34:37], v168 offset:6144
	ds_read_b128 v[66:69], v168 offset:6176
	ds_read_b128 v[70:73], v168 offset:6208
	s_cmp_lt_u32 s75, 13
	s_cselect_b32 s18, 7, 5
	s_waitcnt lgkmcnt(2)
	v_mfma_f32_32x32x16_bf16 v[34:49], v[34:37], v[62:65], 0
	s_cselect_b32 s19, s71, s70
	s_cselect_b32 s28, 4, 1
	s_cselect_b32 s29, 2, 0
	s_cmp_lt_u32 s75, 5
	s_cselect_b32 s18, 9, s18
	s_cselect_b32 s19, s4, s19
	s_cselect_b32 s28, 16, s28
	s_waitcnt lgkmcnt(1)
	v_mfma_f32_32x32x16_bf16 v[34:49], v[66:69], v[58:61], v[34:49]
	s_cselect_b32 s29, 4, s29
	s_lshl_b32 s18, s75, s18
	ds_read_b128 v[66:69], v168 offset:6240
	s_add_i32 s74, s75, 2
	s_add_i32 s76, s18, s19
	s_cmp_lt_u32 s75, 11
	s_cselect_b32 s18, 7, 5
	s_waitcnt lgkmcnt(1)
	v_mfma_f32_32x32x16_bf16 v[34:49], v[70:73], v[54:57], v[34:49]
	s_cselect_b32 s19, s71, s70
	s_cselect_b32 s77, 2, 0
	s_cmp_lt_u32 s75, 3
	s_cselect_b32 s18, 9, s18
	s_cselect_b32 s19, s4, s19
	s_cselect_b32 s77, 4, s77
	s_lshl_b32 s18, s74, s18
	s_add_i32 s78, s18, s19
	v_lshlrev_b32_e32 v1, s77, v164
	v_add_u32_e32 v1, s78, v1
	v_max_i32_e32 v1, s68, v1
	v_min_i32_e32 v1, s69, v1
	s_waitcnt lgkmcnt(0)
	v_mfma_f32_32x32x16_bf16 v[34:49], v[66:69], v[50:53], v[34:49]
	v_mad_u32_u24 v66, v1, s47, v204
	v_lshlrev_b32_e32 v1, s77, v170
	v_add_u32_e32 v1, s78, v1
	v_max_i32_e32 v1, s68, v1
	v_min_i32_e32 v1, s69, v1
	v_mad_u32_u24 v74, v1, s47, v204
	v_lshlrev_b32_e32 v1, s77, v171
	v_add_u32_e32 v1, s78, v1
	v_max_i32_e32 v1, s68, v1
	v_min_i32_e32 v1, s69, v1
	v_mad_u32_u24 v90, v1, s47, v204
	v_lshlrev_b32_e32 v1, s77, v172
	v_add_u32_e32 v1, s78, v1
	v_max_i32_e32 v1, s68, v1
	v_min_i32_e32 v1, s69, v1
	v_mad_u32_u24 v106, v1, s47, v204
	global_load_dwordx4 v[70:73], v66, s[24:25]
	s_nop 0
	global_load_dwordx4 v[66:69], v66, s[24:25] offset:-1024
	s_nop 0
	global_load_dwordx4 v[78:81], v74, s[24:25]
	s_nop 0
	global_load_dwordx4 v[74:77], v74, s[24:25] offset:-1024
	s_nop 0
	global_load_dwordx4 v[94:97], v90, s[24:25]
	s_nop 0
	global_load_dwordx4 v[90:93], v90, s[24:25] offset:-1024
	s_nop 0
	global_load_dwordx4 v[110:113], v106, s[24:25]
	s_nop 0
	global_load_dwordx4 v[106:109], v106, s[24:25] offset:-1024
	s_lshl_b32 s18, s28, 6
	v_cvt_f32_u32_e32 v1, s18
	v_sub_u32_e32 v199, s76, v156
	v_lshl_add_u32 v199, v146, s29, v199
	v_cvt_f32_i32_e32 v199, v199
	v_max_f32_e64 v200, v195, -v1
	v_min_f32_e32 v1, v196, v1
	v_add_f32_e32 v201, v200, v1
	v_sub_f32_e32 v1, v1, v200
	v_cvt_f32_ubyte0_e32 v198, s28
	v_mul_f32_e32 v200, 0.5, v1
	v_fma_f32 v201, -0.5, v201, v199
	v_mul_f32_e32 v1, 0x3e38aa3b, v34
	v_fma_f32 v1, |v199|, v193, v1
	v_cmp_le_f32_e64 vcc, |v201|, v200
	v_add_f32_e32 v34, v198, v199
	v_add_f32_e32 v202, v201, v198
	v_mul_f32_e32 v35, 0x3e38aa3b, v35
	v_cndmask_b32_e32 v1, v192, v1, vcc
	v_fma_f32 v34, |v34|, v193, v35
	v_cmp_le_f32_e64 vcc, |v202|, v200
	v_fma_f32 v35, 2.0, v198, v199
	v_fma_f32 v203, 2.0, v198, v201
	v_mul_f32_e32 v36, 0x3e38aa3b, v36
	v_cndmask_b32_e32 v34, v192, v34, vcc
	v_fma_f32 v35, |v35|, v193, v36
	v_cmp_le_f32_e64 vcc, |v203|, v200
	v_fmamk_f32 v36, v198, 0x40400000, v199
	v_fmamk_f32 v203, v198, 0x40400000, v201
	v_mul_f32_e32 v37, 0x3e38aa3b, v37
	v_cndmask_b32_e32 v35, v192, v35, vcc
	v_fma_f32 v36, |v36|, v193, v37
	v_cmp_le_f32_e64 vcc, |v203|, v200
	v_fmamk_f32 v37, v198, 0x41000000, v199
	v_fmamk_f32 v203, v198, 0x41000000, v201
	v_mul_f32_e32 v38, 0x3e38aa3b, v38
	v_cndmask_b32_e32 v36, v192, v36, vcc
	v_fma_f32 v37, |v37|, v193, v38
	v_cmp_le_f32_e64 vcc, |v203|, v200
	v_fmamk_f32 v38, v198, 0x41100000, v199
	v_fmamk_f32 v203, v198, 0x41100000, v201
	v_mul_f32_e32 v39, 0x3e38aa3b, v39
	v_cndmask_b32_e32 v37, v192, v37, vcc
	v_fma_f32 v38, |v38|, v193, v39
	v_cmp_le_f32_e64 vcc, |v203|, v200
	v_fmamk_f32 v39, v198, 0x41200000, v199
	v_fmamk_f32 v203, v198, 0x41200000, v201
	v_mul_f32_e32 v40, 0x3e38aa3b, v40
	v_cndmask_b32_e32 v38, v192, v38, vcc
	v_fma_f32 v39, |v39|, v193, v40
	v_cmp_le_f32_e64 vcc, |v203|, v200
	v_fmamk_f32 v40, v198, 0x41300000, v199
	v_fmamk_f32 v203, v198, 0x41300000, v201
	v_mul_f32_e32 v41, 0x3e38aa3b, v41
	v_cndmask_b32_e32 v39, v192, v39, vcc
	v_fma_f32 v40, |v40|, v193, v41
	v_cmp_le_f32_e64 vcc, |v203|, v200
	v_fmamk_f32 v41, v198, 0x41800000, v199
	v_fmamk_f32 v203, v198, 0x41800000, v201
	v_mul_f32_e32 v42, 0x3e38aa3b, v42
	v_cndmask_b32_e32 v40, v192, v40, vcc
	v_fma_f32 v41, |v41|, v193, v42
	v_cmp_le_f32_e64 vcc, |v203|, v200
	v_fmamk_f32 v42, v198, 0x41880000, v199
	v_fmamk_f32 v203, v198, 0x41880000, v201
	v_mul_f32_e32 v43, 0x3e38aa3b, v43
	v_cndmask_b32_e32 v41, v192, v41, vcc
	v_fma_f32 v42, |v42|, v193, v43
	v_cmp_le_f32_e64 vcc, |v203|, v200
	v_fmamk_f32 v43, v198, 0x41900000, v199
	v_fmamk_f32 v203, v198, 0x41900000, v201
	v_mul_f32_e32 v44, 0x3e38aa3b, v44
	v_max3_f32 v202, v1, s57, v34
	v_cndmask_b32_e32 v42, v192, v42, vcc
	v_fma_f32 v43, |v43|, v193, v44
	v_cmp_le_f32_e64 vcc, |v203|, v200
	v_fmamk_f32 v44, v198, 0x41980000, v199
	v_fmamk_f32 v203, v198, 0x41980000, v201
	v_mul_f32_e32 v45, 0x3e38aa3b, v45
	v_max3_f32 v202, v202, v35, v36
	v_cndmask_b32_e32 v43, v192, v43, vcc
	v_fma_f32 v44, |v44|, v193, v45
	v_cmp_le_f32_e64 vcc, |v203|, v200
	v_fmamk_f32 v45, v198, 0x41c00000, v199
	v_fmamk_f32 v203, v198, 0x41c00000, v201
	v_mul_f32_e32 v46, 0x3e38aa3b, v46
	v_max3_f32 v202, v202, v37, v38
	v_cndmask_b32_e32 v44, v192, v44, vcc
	v_fma_f32 v45, |v45|, v193, v46
	v_cmp_le_f32_e64 vcc, |v203|, v200
	v_fmamk_f32 v46, v198, 0x41c80000, v199
	v_fmamk_f32 v203, v198, 0x41c80000, v201
	v_mul_f32_e32 v47, 0x3e38aa3b, v47
	ds_read_b64_tr_b16 v[142:143], v163 offset:0
	v_max3_f32 v202, v202, v39, v40
	v_cndmask_b32_e32 v45, v192, v45, vcc
	v_fma_f32 v46, |v46|, v193, v47
	v_cmp_le_f32_e64 vcc, |v203|, v200
	v_fmamk_f32 v47, v198, 0x41d00000, v199
	v_fmamk_f32 v203, v198, 0x41d00000, v201
	v_mul_f32_e32 v48, 0x3e38aa3b, v48
	ds_read_b64_tr_b16 v[144:145], v163 offset:0x600
	v_max3_f32 v202, v202, v41, v42
	v_cndmask_b32_e32 v46, v192, v46, vcc
	v_fma_f32 v47, |v47|, v193, v48
	v_cmp_le_f32_e64 vcc, |v203|, v200
	v_fmac_f32_e32 v199, 0x41d80000, v198
	v_fmac_f32_e32 v201, 0x41d80000, v198
	v_mul_f32_e32 v48, 0x3e38aa3b, v49
	ds_read_b64_tr_b16 v[134:135], v163 offset:64
	v_max3_f32 v202, v202, v43, v44
	v_cndmask_b32_e32 v47, v192, v47, vcc
	v_fma_f32 v48, |v199|, v193, v48
	v_cmp_le_f32_e64 vcc, |v201|, v200
	ds_read_b64_tr_b16 v[136:137], v163 offset:0x640
	v_max3_f32 v202, v202, v45, v46
	ds_read_b64_tr_b16 v[138:139], v163 offset:0xc00
	ds_read_b64_tr_b16 v[140:141], v163 offset:0x1200
	ds_read_b64_tr_b16 v[130:131], v163 offset:0xc40
	s_nop 0
	v_cndmask_b32_e32 v48, v192, v48, vcc
	v_max3_f32 v49, v202, v47, v48
	v_mov_b32_e32 v198, v49
	s_nop 1
	v_permlane32_swap_b32_e32 v49, v198
	ds_read_b64_tr_b16 v[132:133], v163 offset:0x1240
	v_max_f32_e32 v198, v198, v198
	v_max_f32_e32 v49, v49, v49
	v_max_f32_e32 v49, v49, v198
	v_cmp_gt_f32_e32 vcc, v49, v194
	s_cbranch_vccz .LBB0_378
	v_max_f32_e32 v49, v49, v49
	v_max_f32_e32 v198, v194, v194
	v_max_f32_e32 v49, v198, v49
	v_sub_f32_e32 v194, v194, v49
	v_exp_f32_e32 v194, v194
	s_nop 0
	v_pk_mul_f32 v[32:33], v[32:33], v[194:195] op_sel_hi:[1,0]
	v_pk_mul_f32 v[30:31], v[30:31], v[194:195] op_sel_hi:[1,0]
	v_pk_mul_f32 v[28:29], v[28:29], v[194:195] op_sel_hi:[1,0]
	v_pk_mul_f32 v[26:27], v[26:27], v[194:195] op_sel_hi:[1,0]
	v_pk_mul_f32 v[24:25], v[24:25], v[194:195] op_sel_hi:[1,0]
	v_pk_mul_f32 v[22:23], v[22:23], v[194:195] op_sel_hi:[1,0]
	v_pk_mul_f32 v[20:21], v[20:21], v[194:195] op_sel_hi:[1,0]
	v_pk_mul_f32 v[18:19], v[18:19], v[194:195] op_sel_hi:[1,0]
	v_pk_mul_f32 v[16:17], v[16:17], v[194:195] op_sel_hi:[1,0]
	v_pk_mul_f32 v[14:15], v[14:15], v[194:195] op_sel_hi:[1,0]
	v_pk_mul_f32 v[12:13], v[12:13], v[194:195] op_sel_hi:[1,0]
	v_pk_mul_f32 v[10:11], v[10:11], v[194:195] op_sel_hi:[1,0]
	v_pk_mul_f32 v[8:9], v[8:9], v[194:195] op_sel_hi:[1,0]
	v_pk_mul_f32 v[6:7], v[6:7], v[194:195] op_sel_hi:[1,0]
	v_pk_mul_f32 v[4:5], v[4:5], v[194:195] op_sel_hi:[1,0]
	v_pk_mul_f32 v[2:3], v[2:3], v[194:195] op_sel_hi:[1,0]
	v_mul_f32_e32 v197, v197, v194
	v_mov_b32_e32 v194, v49

.LBB0_383:
	v_mov_b32_e32 v82, s77
	v_mad_u32_u24 v98, s76, v164, v82
	s_lshl_b32 s76, s76, 3
	v_add_u32_e32 v114, s76, v98
	v_add_u32_e32 v122, s76, v114
	v_max_i32_e32 v82, s68, v98
	v_max_i32_e32 v98, s68, v114
	v_max_i32_e32 v114, s68, v122
	v_add_u32_e32 v122, s76, v122
	v_max_i32_e32 v122, s68, v122
	v_min_i32_e32 v84, s69, v82
	v_min_i32_e32 v100, s69, v98
	v_min_i32_e32 v116, s69, v114
	v_min_i32_e32 v124, s69, v122
	v_mad_u32_u24 v86, v84, s47, v204
	v_mad_u32_u24 v102, v100, s47, v204
	v_mad_u32_u24 v118, v116, s47, v204
	v_mad_u32_u24 v126, v124, s47, v204
	global_load_dwordx4 v[82:85], v86, s[24:25]
	s_nop 0
	global_load_dwordx4 v[86:89], v86, s[24:25] offset:-1024
	s_nop 0
	global_load_dwordx4 v[98:101], v102, s[24:25]
	s_nop 0
	global_load_dwordx4 v[102:105], v102, s[24:25] offset:-1024
	s_nop 0
	global_load_dwordx4 v[114:117], v118, s[24:25]
	s_nop 0
	global_load_dwordx4 v[118:121], v118, s[24:25] offset:-1024
	s_nop 0
	global_load_dwordx4 v[122:125], v126, s[24:25]
	s_nop 0
	global_load_dwordx4 v[126:129], v126, s[24:25] offset:-1024
